# CONV phase hand-written: weights/bias in registers, 4 tap loads per row in flight, next row prefetched, scalar row addressing
# speedup vs baseline: 1.0105x; 1.0105x over previous
;   __host__ __device__ __forceinline__ bf16_t* ACT() const { return (bf16_t*)(wsl() + OFF_ACT); }
;   __host__ __device__ __forceinline__ bf16_t* XC() const { return (bf16_t*)(wsl() + OFF_FFN); }
; __device__ __forceinline__ uint32_t pack2(float a, float b) { uint32_t r; asm("v_cvt_pk_bf16_f32 %0, %1, %2" : "=v"(r) : "v"(a), "v"(b)); return r; }
; __device__ __forceinline__ float lo2f(uint32_t u) { return __uint_as_float(u << 16); }
; __device__ __forceinline__ float hi2f(uint32_t u) { return __uint_as_float(u & 0xFFFF0000u); }
; __device__ __forceinline__ int otid() { int t = threadIdx.x; asm volatile("" : "+v"(t)); return t; }
; __device__ __forceinline__ int obid() { int t = blockIdx.x; asm volatile("" : "+s"(t)); return t; }
; __device__ __forceinline__ void conv_phase(const Params& p) {
;   const bf16_t* O1 = p.ACT();
;   for (int idx = obid() * NTHR + otid(); idx < NTOK * 128; idx += gridDim.x * NTHR) {
;     int row = idx >> 7, cc = (idx & 127) * 8;
;     int b = row >= TPB ? 1 : 0, u = row - b * TPB;
;     int lo = (u < CTX) ? 0 : CTX, hi = (u < CTX) ? CTX : TPB;
;     float acc[8];
; #pragma unroll
;     for (int e = 0; e < 8; ++e) acc[e] = p.odd_conv_b[cc + e];
; #pragma unroll
;     for (int k = 0; k < 4; ++k) {
;       int uu = u + k - 2;
;       if (uu >= lo && uu < hi) {
;         uint4 v = *(const uint4*)(O1 + (size_t)(row + k - 2) * 2048 + 1024 + cc);
;         const float* wk = p.odd_conv_w + k * 1024 + cc;
;         acc[0] += wk[0] * lo2f(v.x); acc[1] += wk[1] * hi2f(v.x);
;         acc[2] += wk[2] * lo2f(v.y); acc[3] += wk[3] * hi2f(v.y);
;         acc[4] += wk[4] * lo2f(v.z); acc[5] += wk[5] * hi2f(v.z);
;         acc[6] += wk[6] * lo2f(v.w); acc[7] += wk[7] * hi2f(v.w);
;       }
;     }
;     uint4 o;
;     o.x = pack2(acc[0], acc[1]); o.y = pack2(acc[2], acc[3]); o.z = pack2(acc[4], acc[5]); o.w = pack2(acc[6], acc[7]);
;     *(uint4*)(p.XC() + (size_t)row * D + cc) = o;
;   }
.LBB0_287:
	s_andn2_b64 vcc, exec, s[2:3]
	s_cbranch_vccnz .LBB0_325
	s_cmp_gt_i32 s19, 12
	s_mov_b64 s[2:3], -1
	s_cbranch_scc0 .LBB0_301
	s_mov_b64 s[4:5], exec
	s_load_dwordx2 s[6:7], s[0:1], 0xf0
	s_load_dwordx4 s[44:47], s[0:1], 0xa8
	v_lshrrev_b32_e32 v0, 7, v164
	v_and_b32_e32 v1, 0x7f, v164
	v_lshlrev_b32_e32 v2, 4, v1
	v_lshlrev_b32_e32 v3, 5, v1
	v_readfirstlane_b32 s40, v0
	s_lshl_b32 s41, s82, 2
	s_nop 3
	s_add_i32 s42, s41, s40
	s_lshl_b32 s43, s80, 2
	s_waitcnt lgkmcnt(0)
	s_add_u32 s50, s44, 0x1000
	s_addc_u32 s51, s45, 0
	s_add_u32 s52, s44, 0x2000
	s_addc_u32 s53, s45, 0
	s_add_u32 s54, s44, 0x3000
	s_addc_u32 s55, s45, 0
	s_add_u32 s56, s6, 0x728e800
	s_addc_u32 s57, s7, 0
	global_load_dwordx4 v[8:11], v3, s[46:47]
	global_load_dwordx4 v[12:15], v3, s[46:47] offset:16
	global_load_dwordx4 v[16:19], v3, s[44:45]
	global_load_dwordx4 v[20:23], v3, s[44:45] offset:16
	global_load_dwordx4 v[24:27], v3, s[50:51]
	global_load_dwordx4 v[28:31], v3, s[50:51] offset:16
	global_load_dwordx4 v[32:35], v3, s[52:53]
	global_load_dwordx4 v[36:39], v3, s[52:53] offset:16
	global_load_dwordx4 v[40:43], v3, s[54:55]
	global_load_dwordx4 v[44:47], v3, s[54:55] offset:16
	s_cmpk_gt_u32 s42, 0x20ff
	s_cselect_b32 s61, 0x2100, 0
	s_sub_i32 s61, s42, s61
	s_cmpk_lt_u32 s61, 0x100
	s_cselect_b32 s62, 0, 0x100
	s_movk_i32 s63, 0x2100
	s_cselect_b32 s63, 0x100, s63
	s_mov_b32 s59, 0
	s_add_i32 s64, s61, -2
	s_cmp_ge_i32 s64, s62
	s_cselect_b32 s65, 1, 0
	s_cmp_lt_i32 s64, s63
	s_cselect_b32 s66, 1, 0
	s_and_b32 s65, s65, s66
	s_lshl_b32 s66, s65, 0
	s_or_b32 s59, s59, s66
	s_cmp_eq_u32 s65, 1
	s_cselect_b32 s66, 0, 2
	s_add_i32 s66, s42, s66
	s_mov_b32 s67, 0
	s_lshl_b64 s[66:67], s[66:67], 12
	s_add_u32 s66, s66, s56
	s_addc_u32 s67, s67, s57
	global_load_dwordx4 v[48:51], v2, s[66:67]
	s_add_i32 s64, s61, -1
	s_cmp_ge_i32 s64, s62
	s_cselect_b32 s65, 1, 0
	s_cmp_lt_i32 s64, s63
	s_cselect_b32 s66, 1, 0
	s_and_b32 s65, s65, s66
	s_lshl_b32 s66, s65, 1
	s_or_b32 s59, s59, s66
	s_cmp_eq_u32 s65, 1
	s_cselect_b32 s66, 1, 2
	s_add_i32 s66, s42, s66
	s_mov_b32 s67, 0
	s_lshl_b64 s[66:67], s[66:67], 12
	s_add_u32 s66, s66, s56
	s_addc_u32 s67, s67, s57
	global_load_dwordx4 v[52:55], v2, s[66:67]
	s_add_i32 s64, s61, 0
	s_cmp_ge_i32 s64, s62
	s_cselect_b32 s65, 1, 0
	s_cmp_lt_i32 s64, s63
	s_cselect_b32 s66, 1, 0
	s_and_b32 s65, s65, s66
	s_lshl_b32 s66, s65, 2
	s_or_b32 s59, s59, s66
	s_cmp_eq_u32 s65, 1
	s_cselect_b32 s66, 2, 2
	s_add_i32 s66, s42, s66
	s_mov_b32 s67, 0
	s_lshl_b64 s[66:67], s[66:67], 12
	s_add_u32 s66, s66, s56
	s_addc_u32 s67, s67, s57
	global_load_dwordx4 v[56:59], v2, s[66:67]
	s_add_i32 s64, s61, 1
	s_cmp_ge_i32 s64, s62
	s_cselect_b32 s65, 1, 0
	s_cmp_lt_i32 s64, s63
	s_cselect_b32 s66, 1, 0
	s_and_b32 s65, s65, s66
	s_lshl_b32 s66, s65, 3
	s_or_b32 s59, s59, s66
	s_cmp_eq_u32 s65, 1
	s_cselect_b32 s66, 3, 2
	s_add_i32 s66, s42, s66
	s_mov_b32 s67, 0
	s_lshl_b64 s[66:67], s[66:67], 12
	s_add_u32 s66, s66, s56
	s_addc_u32 s67, s67, s57
	global_load_dwordx4 v[60:63], v2, s[66:67]
.Lcv_loop:
	s_add_i32 s58, s42, s43
	s_cmpk_lt_u32 s58, 0x4200
	s_cbranch_scc0 .Lcv_lastA
	s_cmpk_gt_u32 s58, 0x20ff
	s_cselect_b32 s61, 0x2100, 0
	s_sub_i32 s61, s58, s61
	s_cmpk_lt_u32 s61, 0x100
	s_cselect_b32 s62, 0, 0x100
	s_movk_i32 s63, 0x2100
	s_cselect_b32 s63, 0x100, s63
	s_mov_b32 s60, 0
	s_add_i32 s64, s61, -2
	s_cmp_ge_i32 s64, s62
	s_cselect_b32 s65, 1, 0
	s_cmp_lt_i32 s64, s63
	s_cselect_b32 s66, 1, 0
	s_and_b32 s65, s65, s66
	s_lshl_b32 s66, s65, 0
	s_or_b32 s60, s60, s66
	s_cmp_eq_u32 s65, 1
	s_cselect_b32 s66, 0, 2
	s_add_i32 s66, s58, s66
	s_mov_b32 s67, 0
	s_lshl_b64 s[66:67], s[66:67], 12
	s_add_u32 s66, s66, s56
	s_addc_u32 s67, s67, s57
	global_load_dwordx4 v[80:83], v2, s[66:67]
	s_add_i32 s64, s61, -1
	s_cmp_ge_i32 s64, s62
	s_cselect_b32 s65, 1, 0
	s_cmp_lt_i32 s64, s63
	s_cselect_b32 s66, 1, 0
	s_and_b32 s65, s65, s66
	s_lshl_b32 s66, s65, 1
	s_or_b32 s60, s60, s66
	s_cmp_eq_u32 s65, 1
	s_cselect_b32 s66, 1, 2
	s_add_i32 s66, s58, s66
	s_mov_b32 s67, 0
	s_lshl_b64 s[66:67], s[66:67], 12
	s_add_u32 s66, s66, s56
	s_addc_u32 s67, s67, s57
	global_load_dwordx4 v[84:87], v2, s[66:67]
	s_add_i32 s64, s61, 0
	s_cmp_ge_i32 s64, s62
	s_cselect_b32 s65, 1, 0
	s_cmp_lt_i32 s64, s63
	s_cselect_b32 s66, 1, 0
	s_and_b32 s65, s65, s66
	s_lshl_b32 s66, s65, 2
	s_or_b32 s60, s60, s66
	s_cmp_eq_u32 s65, 1
	s_cselect_b32 s66, 2, 2
	s_add_i32 s66, s58, s66
	s_mov_b32 s67, 0
	s_lshl_b64 s[66:67], s[66:67], 12
	s_add_u32 s66, s66, s56
	s_addc_u32 s67, s67, s57
	global_load_dwordx4 v[88:91], v2, s[66:67]
	s_add_i32 s64, s61, 1
	s_cmp_ge_i32 s64, s62
	s_cselect_b32 s65, 1, 0
	s_cmp_lt_i32 s64, s63
	s_cselect_b32 s66, 1, 0
	s_and_b32 s65, s65, s66
	s_lshl_b32 s66, s65, 3
	s_or_b32 s60, s60, s66
	s_cmp_eq_u32 s65, 1
	s_cselect_b32 s66, 3, 2
	s_add_i32 s66, s58, s66
	s_mov_b32 s67, 0
	s_lshl_b64 s[66:67], s[66:67], 12
	s_add_u32 s66, s66, s56
	s_addc_u32 s67, s67, s57
	global_load_dwordx4 v[92:95], v2, s[66:67]
	s_waitcnt vmcnt(4)
	s_bitcmp1_b32 s59, 0
	s_cbranch_scc1 .Lcv_oka0
	v_mov_b32_e32 v48, 0
	v_mov_b32_e32 v49, 0
	v_mov_b32_e32 v50, 0
	v_mov_b32_e32 v51, 0
.Lcv_oka0:
	s_bitcmp1_b32 s59, 1
	s_cbranch_scc1 .Lcv_oka1
	v_mov_b32_e32 v52, 0
	v_mov_b32_e32 v53, 0
	v_mov_b32_e32 v54, 0
	v_mov_b32_e32 v55, 0
.Lcv_oka1:
	s_bitcmp1_b32 s59, 3
	s_cbranch_scc1 .Lcv_oka3
	v_mov_b32_e32 v60, 0
	v_mov_b32_e32 v61, 0
	v_mov_b32_e32 v62, 0
	v_mov_b32_e32 v63, 0
;   __host__ __device__ __forceinline__ bf16_t* XC() const { return (bf16_t*)(wsl() + OFF_FFN); }
; __device__ __forceinline__ uint32_t pack2(float a, float b) { uint32_t r; asm("v_cvt_pk_bf16_f32 %0, %1, %2" : "=v"(r) : "v"(a), "v"(b)); return r; }
; __device__ __forceinline__ float lo2f(uint32_t u) { return __uint_as_float(u << 16); }
; __device__ __forceinline__ float hi2f(uint32_t u) { return __uint_as_float(u & 0xFFFF0000u); }
; __device__ __forceinline__ void conv_phase(const Params& p) {
;     ...
;     float acc[8];
; #pragma unroll
;     for (int e = 0; e < 8; ++e) acc[e] = p.odd_conv_b[cc + e];
; #pragma unroll
;     for (int k = 0; k < 4; ++k) {
;       int uu = u + k - 2;
;       if (uu >= lo && uu < hi) {
;         uint4 v = *(const uint4*)(O1 + (size_t)(row + k - 2) * 2048 + 1024 + cc);
;         const float* wk = p.odd_conv_w + k * 1024 + cc;
;         acc[0] += wk[0] * lo2f(v.x); acc[1] += wk[1] * hi2f(v.x);
;         acc[2] += wk[2] * lo2f(v.y); acc[3] += wk[3] * hi2f(v.y);
;         acc[4] += wk[4] * lo2f(v.z); acc[5] += wk[5] * hi2f(v.z);
;         acc[6] += wk[6] * lo2f(v.w); acc[7] += wk[7] * hi2f(v.w);
;       }
;     }
;     uint4 o;
;     o.x = pack2(acc[0], acc[1]); o.y = pack2(acc[2], acc[3]); o.z = pack2(acc[4], acc[5]); o.w = pack2(acc[6], acc[7]);
;     *(uint4*)(p.XC() + (size_t)row * D + cc) = o;
.Lcv_oka3:
	v_mov_b32_e32 v64, v8
	v_mov_b32_e32 v65, v9
	v_mov_b32_e32 v66, v10
	v_mov_b32_e32 v67, v11
	v_mov_b32_e32 v68, v12
	v_mov_b32_e32 v69, v13
	v_mov_b32_e32 v70, v14
	v_mov_b32_e32 v71, v15
	v_lshlrev_b32_e32 v72, 16, v48
	v_and_b32_e32 v73, 0xffff0000, v48
	v_fmac_f32_e32 v64, v16, v72
	v_fmac_f32_e32 v65, v17, v73
	v_lshlrev_b32_e32 v72, 16, v49
	v_and_b32_e32 v73, 0xffff0000, v49
	v_fmac_f32_e32 v66, v18, v72
	v_fmac_f32_e32 v67, v19, v73
	v_lshlrev_b32_e32 v72, 16, v50
	v_and_b32_e32 v73, 0xffff0000, v50
	v_fmac_f32_e32 v68, v20, v72
	v_fmac_f32_e32 v69, v21, v73
	v_lshlrev_b32_e32 v72, 16, v51
	v_and_b32_e32 v73, 0xffff0000, v51
	v_fmac_f32_e32 v70, v22, v72
	v_fmac_f32_e32 v71, v23, v73
	v_lshlrev_b32_e32 v72, 16, v52
	v_and_b32_e32 v73, 0xffff0000, v52
	v_fmac_f32_e32 v64, v24, v72
	v_fmac_f32_e32 v65, v25, v73
	v_lshlrev_b32_e32 v72, 16, v53
	v_and_b32_e32 v73, 0xffff0000, v53
	v_fmac_f32_e32 v66, v26, v72
	v_fmac_f32_e32 v67, v27, v73
	v_lshlrev_b32_e32 v72, 16, v54
	v_and_b32_e32 v73, 0xffff0000, v54
	v_fmac_f32_e32 v68, v28, v72
	v_fmac_f32_e32 v69, v29, v73
	v_lshlrev_b32_e32 v72, 16, v55
	v_and_b32_e32 v73, 0xffff0000, v55
	v_fmac_f32_e32 v70, v30, v72
	v_fmac_f32_e32 v71, v31, v73
	v_lshlrev_b32_e32 v72, 16, v56
	v_and_b32_e32 v73, 0xffff0000, v56
	v_fmac_f32_e32 v64, v32, v72
	v_fmac_f32_e32 v65, v33, v73
	v_lshlrev_b32_e32 v72, 16, v57
	v_and_b32_e32 v73, 0xffff0000, v57
	v_fmac_f32_e32 v66, v34, v72
	v_fmac_f32_e32 v67, v35, v73
	v_lshlrev_b32_e32 v72, 16, v58
	v_and_b32_e32 v73, 0xffff0000, v58
	v_fmac_f32_e32 v68, v36, v72
	v_fmac_f32_e32 v69, v37, v73
	v_lshlrev_b32_e32 v72, 16, v59
	v_and_b32_e32 v73, 0xffff0000, v59
	v_fmac_f32_e32 v70, v38, v72
	v_fmac_f32_e32 v71, v39, v73
	v_lshlrev_b32_e32 v72, 16, v60
	v_and_b32_e32 v73, 0xffff0000, v60
	v_fmac_f32_e32 v64, v40, v72
	v_fmac_f32_e32 v65, v41, v73
	v_lshlrev_b32_e32 v72, 16, v61
	v_and_b32_e32 v73, 0xffff0000, v61
	v_fmac_f32_e32 v66, v42, v72
	v_fmac_f32_e32 v67, v43, v73
	v_lshlrev_b32_e32 v72, 16, v62
	v_and_b32_e32 v73, 0xffff0000, v62
	v_fmac_f32_e32 v68, v44, v72
	v_fmac_f32_e32 v69, v45, v73
	v_lshlrev_b32_e32 v72, 16, v63
	v_and_b32_e32 v73, 0xffff0000, v63
	v_fmac_f32_e32 v70, v46, v72
	v_fmac_f32_e32 v71, v47, v73
	v_cvt_pk_bf16_f32 v74, v64, v65
	v_cvt_pk_bf16_f32 v75, v66, v67
	v_cvt_pk_bf16_f32 v76, v68, v69
	v_cvt_pk_bf16_f32 v77, v70, v71
	s_mov_b32 s66, s42
	s_mov_b32 s67, 0
	s_lshl_b64 s[66:67], s[66:67], 11
	s_add_u32 s66, s66, s6
	s_addc_u32 s67, s67, s7
	global_store_dwordx4 v2, v[74:77], s[66:67]
	s_add_i32 s42, s58, s43
	s_cmpk_lt_u32 s42, 0x4200
	s_cbranch_scc0 .Lcv_lastB
	s_cmpk_gt_u32 s42, 0x20ff
	s_cselect_b32 s61, 0x2100, 0
	s_sub_i32 s61, s42, s61
	s_cmpk_lt_u32 s61, 0x100
	s_cselect_b32 s62, 0, 0x100
	s_movk_i32 s63, 0x2100
	s_cselect_b32 s63, 0x100, s63
	s_mov_b32 s59, 0
	s_add_i32 s64, s61, -2
	s_cmp_ge_i32 s64, s62
	s_cselect_b32 s65, 1, 0
	s_cmp_lt_i32 s64, s63
	s_cselect_b32 s66, 1, 0
	s_and_b32 s65, s65, s66
	s_lshl_b32 s66, s65, 0
	s_or_b32 s59, s59, s66
	s_cmp_eq_u32 s65, 1
	s_cselect_b32 s66, 0, 2
	s_add_i32 s66, s42, s66
	s_mov_b32 s67, 0
	s_lshl_b64 s[66:67], s[66:67], 12
	s_add_u32 s66, s66, s56
	s_addc_u32 s67, s67, s57
	global_load_dwordx4 v[48:51], v2, s[66:67]
	s_add_i32 s64, s61, -1
	s_cmp_ge_i32 s64, s62
	s_cselect_b32 s65, 1, 0
	s_cmp_lt_i32 s64, s63
	s_cselect_b32 s66, 1, 0
	s_and_b32 s65, s65, s66
	s_lshl_b32 s66, s65, 1
	s_or_b32 s59, s59, s66
	s_cmp_eq_u32 s65, 1
	s_cselect_b32 s66, 1, 2
	s_add_i32 s66, s42, s66
	s_mov_b32 s67, 0
	s_lshl_b64 s[66:67], s[66:67], 12
	s_add_u32 s66, s66, s56
	s_addc_u32 s67, s67, s57
	global_load_dwordx4 v[52:55], v2, s[66:67]
	s_add_i32 s64, s61, 0
	s_cmp_ge_i32 s64, s62
	s_cselect_b32 s65, 1, 0
	s_cmp_lt_i32 s64, s63
	s_cselect_b32 s66, 1, 0
	s_and_b32 s65, s65, s66
	s_lshl_b32 s66, s65, 2
	s_or_b32 s59, s59, s66
	s_cmp_eq_u32 s65, 1
	s_cselect_b32 s66, 2, 2
	s_add_i32 s66, s42, s66
	s_mov_b32 s67, 0
	s_lshl_b64 s[66:67], s[66:67], 12
	s_add_u32 s66, s66, s56
	s_addc_u32 s67, s67, s57
	global_load_dwordx4 v[56:59], v2, s[66:67]
	s_add_i32 s64, s61, 1
	s_cmp_ge_i32 s64, s62
	s_cselect_b32 s65, 1, 0
	s_cmp_lt_i32 s64, s63
	s_cselect_b32 s66, 1, 0
	s_and_b32 s65, s65, s66
	s_lshl_b32 s66, s65, 3
	s_or_b32 s59, s59, s66
	s_cmp_eq_u32 s65, 1
	s_cselect_b32 s66, 3, 2
	s_add_i32 s66, s42, s66
	s_mov_b32 s67, 0
	s_lshl_b64 s[66:67], s[66:67], 12
	s_add_u32 s66, s66, s56
	s_addc_u32 s67, s67, s57
	global_load_dwordx4 v[60:63], v2, s[66:67]
	s_waitcnt vmcnt(4)
	s_bitcmp1_b32 s60, 0
	s_cbranch_scc1 .Lcv_okb0
	v_mov_b32_e32 v80, 0
	v_mov_b32_e32 v81, 0
	v_mov_b32_e32 v82, 0
	v_mov_b32_e32 v83, 0
;   __host__ __device__ __forceinline__ bf16_t* XC() const { return (bf16_t*)(wsl() + OFF_FFN); }
; __device__ __forceinline__ uint32_t pack2(float a, float b) { uint32_t r; asm("v_cvt_pk_bf16_f32 %0, %1, %2" : "=v"(r) : "v"(a), "v"(b)); return r; }
; __device__ __forceinline__ float lo2f(uint32_t u) { return __uint_as_float(u << 16); }
; __device__ __forceinline__ float hi2f(uint32_t u) { return __uint_as_float(u & 0xFFFF0000u); }
; __device__ __forceinline__ void conv_phase(const Params& p) {
;     ...
;     float acc[8];
; #pragma unroll
;     for (int e = 0; e < 8; ++e) acc[e] = p.odd_conv_b[cc + e];
; #pragma unroll
;     for (int k = 0; k < 4; ++k) {
;       int uu = u + k - 2;
;       if (uu >= lo && uu < hi) {
;         uint4 v = *(const uint4*)(O1 + (size_t)(row + k - 2) * 2048 + 1024 + cc);
;         const float* wk = p.odd_conv_w + k * 1024 + cc;
;         acc[0] += wk[0] * lo2f(v.x); acc[1] += wk[1] * hi2f(v.x);
;         acc[2] += wk[2] * lo2f(v.y); acc[3] += wk[3] * hi2f(v.y);
;         acc[4] += wk[4] * lo2f(v.z); acc[5] += wk[5] * hi2f(v.z);
;         acc[6] += wk[6] * lo2f(v.w); acc[7] += wk[7] * hi2f(v.w);
;       }
;     }
;     uint4 o;
;     o.x = pack2(acc[0], acc[1]); o.y = pack2(acc[2], acc[3]); o.z = pack2(acc[4], acc[5]); o.w = pack2(acc[6], acc[7]);
;     *(uint4*)(p.XC() + (size_t)row * D + cc) = o;
.Lcv_okb0:
	s_bitcmp1_b32 s60, 1
	s_cbranch_scc1 .Lcv_okb1
	v_mov_b32_e32 v84, 0
	v_mov_b32_e32 v85, 0
	v_mov_b32_e32 v86, 0
	v_mov_b32_e32 v87, 0
.Lcv_okb1:
	s_bitcmp1_b32 s60, 3
	s_cbranch_scc1 .Lcv_okb3
	v_mov_b32_e32 v92, 0
	v_mov_b32_e32 v93, 0
	v_mov_b32_e32 v94, 0
	v_mov_b32_e32 v95, 0
.Lcv_okb3:
	v_mov_b32_e32 v64, v8
	v_mov_b32_e32 v65, v9
	v_mov_b32_e32 v66, v10
	v_mov_b32_e32 v67, v11
	v_mov_b32_e32 v68, v12
	v_mov_b32_e32 v69, v13
	v_mov_b32_e32 v70, v14
	v_mov_b32_e32 v71, v15
	v_lshlrev_b32_e32 v72, 16, v80
	v_and_b32_e32 v73, 0xffff0000, v80
	v_fmac_f32_e32 v64, v16, v72
	v_fmac_f32_e32 v65, v17, v73
	v_lshlrev_b32_e32 v72, 16, v81
	v_and_b32_e32 v73, 0xffff0000, v81
	v_fmac_f32_e32 v66, v18, v72
	v_fmac_f32_e32 v67, v19, v73
	v_lshlrev_b32_e32 v72, 16, v82
	v_and_b32_e32 v73, 0xffff0000, v82
	v_fmac_f32_e32 v68, v20, v72
	v_fmac_f32_e32 v69, v21, v73
	v_lshlrev_b32_e32 v72, 16, v83
	v_and_b32_e32 v73, 0xffff0000, v83
	v_fmac_f32_e32 v70, v22, v72
	v_fmac_f32_e32 v71, v23, v73
	v_lshlrev_b32_e32 v72, 16, v84
	v_and_b32_e32 v73, 0xffff0000, v84
	v_fmac_f32_e32 v64, v24, v72
	v_fmac_f32_e32 v65, v25, v73
	v_lshlrev_b32_e32 v72, 16, v85
	v_and_b32_e32 v73, 0xffff0000, v85
	v_fmac_f32_e32 v66, v26, v72
	v_fmac_f32_e32 v67, v27, v73
	v_lshlrev_b32_e32 v72, 16, v86
	v_and_b32_e32 v73, 0xffff0000, v86
	v_fmac_f32_e32 v68, v28, v72
	v_fmac_f32_e32 v69, v29, v73
	v_lshlrev_b32_e32 v72, 16, v87
	v_and_b32_e32 v73, 0xffff0000, v87
	v_fmac_f32_e32 v70, v30, v72
	v_fmac_f32_e32 v71, v31, v73
	v_lshlrev_b32_e32 v72, 16, v88
	v_and_b32_e32 v73, 0xffff0000, v88
	v_fmac_f32_e32 v64, v32, v72
	v_fmac_f32_e32 v65, v33, v73
	v_lshlrev_b32_e32 v72, 16, v89
	v_and_b32_e32 v73, 0xffff0000, v89
	v_fmac_f32_e32 v66, v34, v72
	v_fmac_f32_e32 v67, v35, v73
	v_lshlrev_b32_e32 v72, 16, v90
	v_and_b32_e32 v73, 0xffff0000, v90
	v_fmac_f32_e32 v68, v36, v72
	v_fmac_f32_e32 v69, v37, v73
	v_lshlrev_b32_e32 v72, 16, v91
	v_and_b32_e32 v73, 0xffff0000, v91
	v_fmac_f32_e32 v70, v38, v72
	v_fmac_f32_e32 v71, v39, v73
	v_lshlrev_b32_e32 v72, 16, v92
	v_and_b32_e32 v73, 0xffff0000, v92
	v_fmac_f32_e32 v64, v40, v72
	v_fmac_f32_e32 v65, v41, v73
	v_lshlrev_b32_e32 v72, 16, v93
	v_and_b32_e32 v73, 0xffff0000, v93
	v_fmac_f32_e32 v66, v42, v72
	v_fmac_f32_e32 v67, v43, v73
	v_lshlrev_b32_e32 v72, 16, v94
	v_and_b32_e32 v73, 0xffff0000, v94
	v_fmac_f32_e32 v68, v44, v72
	v_fmac_f32_e32 v69, v45, v73
	v_lshlrev_b32_e32 v72, 16, v95
	v_and_b32_e32 v73, 0xffff0000, v95
	v_fmac_f32_e32 v70, v46, v72
	v_fmac_f32_e32 v71, v47, v73
	v_cvt_pk_bf16_f32 v74, v64, v65
	v_cvt_pk_bf16_f32 v75, v66, v67
	v_cvt_pk_bf16_f32 v76, v68, v69
	v_cvt_pk_bf16_f32 v77, v70, v71
	s_mov_b32 s66, s58
	s_mov_b32 s67, 0
	s_lshl_b64 s[66:67], s[66:67], 11
	s_add_u32 s66, s66, s6
	s_addc_u32 s67, s67, s7
	global_store_dwordx4 v2, v[74:77], s[66:67]
	s_branch .Lcv_loop
.Lcv_lastA:
	s_waitcnt vmcnt(0)
	s_bitcmp1_b32 s59, 0
	s_cbranch_scc1 .Lcv_okc0
	v_mov_b32_e32 v48, 0
	v_mov_b32_e32 v49, 0
	v_mov_b32_e32 v50, 0
	v_mov_b32_e32 v51, 0

;   __host__ __device__ __forceinline__ bf16_t* XC() const { return (bf16_t*)(wsl() + OFF_FFN); }
; __device__ __forceinline__ uint32_t pack2(float a, float b) { uint32_t r; asm("v_cvt_pk_bf16_f32 %0, %1, %2" : "=v"(r) : "v"(a), "v"(b)); return r; }
; __device__ __forceinline__ float lo2f(uint32_t u) { return __uint_as_float(u << 16); }
; __device__ __forceinline__ float hi2f(uint32_t u) { return __uint_as_float(u & 0xFFFF0000u); }
; __device__ __forceinline__ void conv_phase(const Params& p) {
;     ...
;     float acc[8];
; #pragma unroll
;     for (int e = 0; e < 8; ++e) acc[e] = p.odd_conv_b[cc + e];
; #pragma unroll
;     for (int k = 0; k < 4; ++k) {
;       int uu = u + k - 2;
;       if (uu >= lo && uu < hi) {
;         uint4 v = *(const uint4*)(O1 + (size_t)(row + k - 2) * 2048 + 1024 + cc);
;         const float* wk = p.odd_conv_w + k * 1024 + cc;
;         acc[0] += wk[0] * lo2f(v.x); acc[1] += wk[1] * hi2f(v.x);
;         acc[2] += wk[2] * lo2f(v.y); acc[3] += wk[3] * hi2f(v.y);
;         acc[4] += wk[4] * lo2f(v.z); acc[5] += wk[5] * hi2f(v.z);
;         acc[6] += wk[6] * lo2f(v.w); acc[7] += wk[7] * hi2f(v.w);
;       }
;     }
;     uint4 o;
;     o.x = pack2(acc[0], acc[1]); o.y = pack2(acc[2], acc[3]); o.z = pack2(acc[4], acc[5]); o.w = pack2(acc[6], acc[7]);
;     *(uint4*)(p.XC() + (size_t)row * D + cc) = o;
.Lcv_okc3:
	v_mov_b32_e32 v64, v8
	v_mov_b32_e32 v65, v9
	v_mov_b32_e32 v66, v10
	v_mov_b32_e32 v67, v11
	v_mov_b32_e32 v68, v12
	v_mov_b32_e32 v69, v13
	v_mov_b32_e32 v70, v14
	v_mov_b32_e32 v71, v15
	v_lshlrev_b32_e32 v72, 16, v48
	v_and_b32_e32 v73, 0xffff0000, v48
	v_fmac_f32_e32 v64, v16, v72
	v_fmac_f32_e32 v65, v17, v73
	v_lshlrev_b32_e32 v72, 16, v49
	v_and_b32_e32 v73, 0xffff0000, v49
	v_fmac_f32_e32 v66, v18, v72
	v_fmac_f32_e32 v67, v19, v73
	v_lshlrev_b32_e32 v72, 16, v50
	v_and_b32_e32 v73, 0xffff0000, v50
	v_fmac_f32_e32 v68, v20, v72
	v_fmac_f32_e32 v69, v21, v73
	v_lshlrev_b32_e32 v72, 16, v51
	v_and_b32_e32 v73, 0xffff0000, v51
	v_fmac_f32_e32 v70, v22, v72
	v_fmac_f32_e32 v71, v23, v73
	v_lshlrev_b32_e32 v72, 16, v52
	v_and_b32_e32 v73, 0xffff0000, v52
	v_fmac_f32_e32 v64, v24, v72
	v_fmac_f32_e32 v65, v25, v73
	v_lshlrev_b32_e32 v72, 16, v53
	v_and_b32_e32 v73, 0xffff0000, v53
	v_fmac_f32_e32 v66, v26, v72
	v_fmac_f32_e32 v67, v27, v73
	v_lshlrev_b32_e32 v72, 16, v54
	v_and_b32_e32 v73, 0xffff0000, v54
	v_fmac_f32_e32 v68, v28, v72
	v_fmac_f32_e32 v69, v29, v73
	v_lshlrev_b32_e32 v72, 16, v55
	v_and_b32_e32 v73, 0xffff0000, v55
	v_fmac_f32_e32 v70, v30, v72
	v_fmac_f32_e32 v71, v31, v73
	v_lshlrev_b32_e32 v72, 16, v56
	v_and_b32_e32 v73, 0xffff0000, v56
	v_fmac_f32_e32 v64, v32, v72
	v_fmac_f32_e32 v65, v33, v73
	v_lshlrev_b32_e32 v72, 16, v57
	v_and_b32_e32 v73, 0xffff0000, v57
	v_fmac_f32_e32 v66, v34, v72
	v_fmac_f32_e32 v67, v35, v73
	v_lshlrev_b32_e32 v72, 16, v58
	v_and_b32_e32 v73, 0xffff0000, v58
	v_fmac_f32_e32 v68, v36, v72
	v_fmac_f32_e32 v69, v37, v73
	v_lshlrev_b32_e32 v72, 16, v59
	v_and_b32_e32 v73, 0xffff0000, v59
	v_fmac_f32_e32 v70, v38, v72
	v_fmac_f32_e32 v71, v39, v73
	v_lshlrev_b32_e32 v72, 16, v60
	v_and_b32_e32 v73, 0xffff0000, v60
	v_fmac_f32_e32 v64, v40, v72
	v_fmac_f32_e32 v65, v41, v73
	v_lshlrev_b32_e32 v72, 16, v61
	v_and_b32_e32 v73, 0xffff0000, v61
	v_fmac_f32_e32 v66, v42, v72
	v_fmac_f32_e32 v67, v43, v73
	v_lshlrev_b32_e32 v72, 16, v62
	v_and_b32_e32 v73, 0xffff0000, v62
	v_fmac_f32_e32 v68, v44, v72
	v_fmac_f32_e32 v69, v45, v73
	v_lshlrev_b32_e32 v72, 16, v63
	v_and_b32_e32 v73, 0xffff0000, v63
	v_fmac_f32_e32 v70, v46, v72
	v_fmac_f32_e32 v71, v47, v73
	v_cvt_pk_bf16_f32 v74, v64, v65
	v_cvt_pk_bf16_f32 v75, v66, v67
	v_cvt_pk_bf16_f32 v76, v68, v69
	v_cvt_pk_bf16_f32 v77, v70, v71
	s_mov_b32 s66, s42
	s_mov_b32 s67, 0
	s_lshl_b64 s[66:67], s[66:67], 11
	s_add_u32 s66, s66, s6
	s_addc_u32 s67, s67, s7
	global_store_dwordx4 v2, v[74:77], s[66:67]
	s_branch .Lcv_done
.Lcv_lastB:
	s_waitcnt vmcnt(0)
	s_bitcmp1_b32 s60, 0
	s_cbranch_scc1 .Lcv_okd0
	v_mov_b32_e32 v80, 0
	v_mov_b32_e32 v81, 0
	v_mov_b32_e32 v82, 0
	v_mov_b32_e32 v83, 0

;   __host__ __device__ __forceinline__ bf16_t* XC() const { return (bf16_t*)(wsl() + OFF_FFN); }
; __device__ __forceinline__ uint32_t pack2(float a, float b) { uint32_t r; asm("v_cvt_pk_bf16_f32 %0, %1, %2" : "=v"(r) : "v"(a), "v"(b)); return r; }
; __device__ __forceinline__ float lo2f(uint32_t u) { return __uint_as_float(u << 16); }
; __device__ __forceinline__ float hi2f(uint32_t u) { return __uint_as_float(u & 0xFFFF0000u); }
; __device__ __forceinline__ void conv_phase(const Params& p) {
;     ...
;     float acc[8];
; #pragma unroll
;     for (int e = 0; e < 8; ++e) acc[e] = p.odd_conv_b[cc + e];
; #pragma unroll
;     for (int k = 0; k < 4; ++k) {
;       int uu = u + k - 2;
;       if (uu >= lo && uu < hi) {
;         uint4 v = *(const uint4*)(O1 + (size_t)(row + k - 2) * 2048 + 1024 + cc);
;         const float* wk = p.odd_conv_w + k * 1024 + cc;
;         acc[0] += wk[0] * lo2f(v.x); acc[1] += wk[1] * hi2f(v.x);
;         acc[2] += wk[2] * lo2f(v.y); acc[3] += wk[3] * hi2f(v.y);
;         acc[4] += wk[4] * lo2f(v.z); acc[5] += wk[5] * hi2f(v.z);
;         acc[6] += wk[6] * lo2f(v.w); acc[7] += wk[7] * hi2f(v.w);
;       }
;     }
;     uint4 o;
;     o.x = pack2(acc[0], acc[1]); o.y = pack2(acc[2], acc[3]); o.z = pack2(acc[4], acc[5]); o.w = pack2(acc[6], acc[7]);
;     *(uint4*)(p.XC() + (size_t)row * D + cc) = o;
.Lcv_okd3:
	v_mov_b32_e32 v64, v8
	v_mov_b32_e32 v65, v9
	v_mov_b32_e32 v66, v10
	v_mov_b32_e32 v67, v11
	v_mov_b32_e32 v68, v12
	v_mov_b32_e32 v69, v13
	v_mov_b32_e32 v70, v14
	v_mov_b32_e32 v71, v15
	v_lshlrev_b32_e32 v72, 16, v80
	v_and_b32_e32 v73, 0xffff0000, v80
	v_fmac_f32_e32 v64, v16, v72
	v_fmac_f32_e32 v65, v17, v73
	v_lshlrev_b32_e32 v72, 16, v81
	v_and_b32_e32 v73, 0xffff0000, v81
	v_fmac_f32_e32 v66, v18, v72
	v_fmac_f32_e32 v67, v19, v73
	v_lshlrev_b32_e32 v72, 16, v82
	v_and_b32_e32 v73, 0xffff0000, v82
	v_fmac_f32_e32 v68, v20, v72
	v_fmac_f32_e32 v69, v21, v73
	v_lshlrev_b32_e32 v72, 16, v83
	v_and_b32_e32 v73, 0xffff0000, v83
	v_fmac_f32_e32 v70, v22, v72
	v_fmac_f32_e32 v71, v23, v73
	v_lshlrev_b32_e32 v72, 16, v84
	v_and_b32_e32 v73, 0xffff0000, v84
	v_fmac_f32_e32 v64, v24, v72
	v_fmac_f32_e32 v65, v25, v73
	v_lshlrev_b32_e32 v72, 16, v85
	v_and_b32_e32 v73, 0xffff0000, v85
	v_fmac_f32_e32 v66, v26, v72
	v_fmac_f32_e32 v67, v27, v73
	v_lshlrev_b32_e32 v72, 16, v86
	v_and_b32_e32 v73, 0xffff0000, v86
	v_fmac_f32_e32 v68, v28, v72
	v_fmac_f32_e32 v69, v29, v73
	v_lshlrev_b32_e32 v72, 16, v87
	v_and_b32_e32 v73, 0xffff0000, v87
	v_fmac_f32_e32 v70, v30, v72
	v_fmac_f32_e32 v71, v31, v73
	v_lshlrev_b32_e32 v72, 16, v88
	v_and_b32_e32 v73, 0xffff0000, v88
	v_fmac_f32_e32 v64, v32, v72
	v_fmac_f32_e32 v65, v33, v73
	v_lshlrev_b32_e32 v72, 16, v89
	v_and_b32_e32 v73, 0xffff0000, v89
	v_fmac_f32_e32 v66, v34, v72
	v_fmac_f32_e32 v67, v35, v73
	v_lshlrev_b32_e32 v72, 16, v90
	v_and_b32_e32 v73, 0xffff0000, v90
	v_fmac_f32_e32 v68, v36, v72
	v_fmac_f32_e32 v69, v37, v73
	v_lshlrev_b32_e32 v72, 16, v91
	v_and_b32_e32 v73, 0xffff0000, v91
	v_fmac_f32_e32 v70, v38, v72
	v_fmac_f32_e32 v71, v39, v73
	v_lshlrev_b32_e32 v72, 16, v92
	v_and_b32_e32 v73, 0xffff0000, v92
	v_fmac_f32_e32 v64, v40, v72
	v_fmac_f32_e32 v65, v41, v73
	v_lshlrev_b32_e32 v72, 16, v93
	v_and_b32_e32 v73, 0xffff0000, v93
	v_fmac_f32_e32 v66, v42, v72
	v_fmac_f32_e32 v67, v43, v73
	v_lshlrev_b32_e32 v72, 16, v94
	v_and_b32_e32 v73, 0xffff0000, v94
	v_fmac_f32_e32 v68, v44, v72
	v_fmac_f32_e32 v69, v45, v73
	v_lshlrev_b32_e32 v72, 16, v95
	v_and_b32_e32 v73, 0xffff0000, v95
	v_fmac_f32_e32 v70, v46, v72
	v_fmac_f32_e32 v71, v47, v73
	v_cvt_pk_bf16_f32 v74, v64, v65
	v_cvt_pk_bf16_f32 v75, v66, v67
	v_cvt_pk_bf16_f32 v76, v68, v69
	v_cvt_pk_bf16_f32 v77, v70, v71
	s_mov_b32 s66, s58
	s_mov_b32 s67, 0
	s_lshl_b64 s[66:67], s[66:67], 11
	s_add_u32 s66, s66, s6
	s_addc_u32 s67, s67, s7
	global_store_dwordx4 v2, v[74:77], s[66:67]
.Lcv_done:
.LBB0_300:
	s_or_b64 exec, exec, s[4:5]
	s_mov_b64 s[2:3], 0
